# P0: software bf16 RNE bit-trick (6 VALU per pair) replaced by v_cvt_pk_bf16_f32 in 108 places (bit-identical for finite inputs), on top of v23
# speedup vs baseline: 1.0091x; 1.0064x over previous
; #define GAS __attribute__((address_space(1)))
; #define LAS __attribute__((address_space(3)))
; #define LDS_WAIT() asm volatile("s_waitcnt lgkmcnt(0)" ::: "memory")
; __device__ __forceinline__ unsigned f2bf(float f) { unsigned u = __builtin_bit_cast(unsigned, f); return (u + 0x7fffu + ((u >> 16) & 1u)) >> 16; }
; __device__ __forceinline__ unsigned pk2(float lo, float hi) { return f2bf(lo) | (f2bf(hi) << 16); }
; __device__ __forceinline__ void p0_item_store(const P0Item& I, const float (&wv)[32], LAS float* scr, int lane) {
; #pragma unroll
;     for (int i = 0; i < 8; ++i) { const int kk = 8 * i + (lane >> 3); const float s = I.scale ? I.scale[I.k0 + kk] : 1.f; LAS float* d = scr + kk * 33 + 4 * (lane & 7);
;         d[0] = wv[4 * i] * s; d[1] = wv[4 * i + 1] * s; d[2] = wv[4 * i + 2] * s; d[3] = wv[4 * i + 3] * s; }
;     LDS_WAIT(); asm volatile("" ::: "memory");
;     const int c = lane & 7;
; #pragma unroll
;     for (int j = 0; j < 4; ++j) { const int n = (lane >> 3) + 8 * j; const int ns = I.perm ? rope_perm(n) : n; const LAS float* s = scr + (8 * c) * 33 + ns;
;         v4u o; o.x = pk2(s[0 * 33], s[1 * 33]); o.y = pk2(s[2 * 33], s[3 * 33]); o.z = pk2(s[4 * 33], s[5 * 33]); o.w = pk2(s[6 * 33], s[7 * 33]);
;         *(GAS v4u*)(I.WT + (size_t)(I.out_row0 + n) * I.K + I.k0 + 8 * c) = o; }
;     LDS_WAIT(); asm volatile("" ::: "memory");
.LBB0_47:
	s_waitcnt vmcnt(0)
	v_pk_mul_f32 v[96:97], v[96:97], v[104:105] op_sel_hi:[1,0]
	ds_write2_b32 v139, v96, v97 offset1:1
	v_pk_mul_f32 v[96:97], v[98:99], v[104:105] op_sel_hi:[1,0]
	ds_write2_b32 v140, v96, v97 offset1:1
	s_and_b64 vcc, s[0:1], s[84:85]
	s_waitcnt lgkmcnt(0)
	v_cndmask_b32_e32 v96, v132, v154, vcc
	v_lshl_add_u32 v102, v96, 2, v153
	ds_read2_b32 v[96:97], v102 offset1:33
	s_and_b64 vcc, s[2:3], s[84:85]
	s_lshl_b64 s[8:9], s[86:87], 1
	s_waitcnt lgkmcnt(0)
	ds_read2_b32 v[98:99], v102 offset0:66 offset1:99
	ds_read2_b32 v[100:101], v102 offset0:132 offset1:165
	v_cvt_pk_bf16_f32 v96, v96, v97
	s_waitcnt lgkmcnt(1)
	ds_read2_b32 v[102:103], v102 offset0:198 offset1:231
	v_cvt_pk_bf16_f32 v97, v98, v99
	s_waitcnt lgkmcnt(1)
	v_cvt_pk_bf16_f32 v98, v100, v101
	s_waitcnt lgkmcnt(0)
	v_cvt_pk_bf16_f32 v99, v102, v103
	v_add_u32_e32 v100, s94, v132
	v_ashrrev_i32_e32 v101, 31, v100
	v_cndmask_b32_e32 v102, v149, v155, vcc
	v_lshlrev_b64 v[100:101], 11, v[100:101]
	v_lshl_add_u32 v104, v102, 2, v153
	v_lshl_add_u64 v[100:101], s[78:79], 0, v[100:101]
	ds_read2_b32 v[102:103], v104 offset1:33
	v_lshl_add_u64 v[100:101], v[100:101], 0, s[8:9]
	v_lshl_add_u64 v[100:101], v[100:101], 0, v[134:135]
	global_store_dwordx4 v[100:101], v[96:99], off
	ds_read2_b32 v[98:99], v104 offset0:66 offset1:99
	ds_read2_b32 v[100:101], v104 offset0:132 offset1:165
	s_waitcnt lgkmcnt(2)
	v_cvt_pk_bf16_f32 v96, v102, v103
	s_waitcnt lgkmcnt(1)
	ds_read2_b32 v[102:103], v104 offset0:198 offset1:231
	v_cvt_pk_bf16_f32 v97, v98, v99
	s_waitcnt lgkmcnt(1)
	v_cvt_pk_bf16_f32 v98, v100, v101
	s_waitcnt lgkmcnt(0)
	v_cvt_pk_bf16_f32 v99, v102, v103
	v_add_u32_e32 v100, s94, v149
	s_and_b64 vcc, s[4:5], s[84:85]
	v_ashrrev_i32_e32 v101, 31, v100
	v_cndmask_b32_e32 v102, v151, v156, vcc
	v_lshlrev_b64 v[100:101], 11, v[100:101]
	v_lshl_add_u32 v104, v102, 2, v153
	ds_read2_b32 v[102:103], v104 offset1:33
	v_lshl_add_u64 v[100:101], s[78:79], 0, v[100:101]
	v_lshl_add_u64 v[100:101], v[100:101], 0, s[8:9]
	v_lshl_add_u64 v[100:101], v[100:101], 0, v[134:135]
	global_store_dwordx4 v[100:101], v[96:99], off
	ds_read2_b32 v[98:99], v104 offset0:66 offset1:99
	ds_read2_b32 v[100:101], v104 offset0:132 offset1:165
	s_waitcnt lgkmcnt(2)
	v_cvt_pk_bf16_f32 v96, v102, v103
	s_waitcnt lgkmcnt(1)
	ds_read2_b32 v[102:103], v104 offset0:198 offset1:231
	v_cvt_pk_bf16_f32 v97, v98, v99
	s_waitcnt lgkmcnt(1)
	v_cvt_pk_bf16_f32 v98, v100, v101
	s_waitcnt lgkmcnt(0)
	v_cvt_pk_bf16_f32 v99, v102, v103
	v_add_u32_e32 v100, s94, v151
	s_and_b64 vcc, s[6:7], s[84:85]
	v_ashrrev_i32_e32 v101, 31, v100
	v_cndmask_b32_e32 v102, v152, v157, vcc
	v_lshlrev_b64 v[100:101], 11, v[100:101]
	v_lshl_add_u32 v104, v102, 2, v153
	ds_read2_b32 v[102:103], v104 offset1:33
	v_lshl_add_u64 v[100:101], s[78:79], 0, v[100:101]
	v_lshl_add_u64 v[100:101], v[100:101], 0, s[8:9]
	v_lshl_add_u64 v[100:101], v[100:101], 0, v[134:135]
	global_store_dwordx4 v[100:101], v[96:99], off
	ds_read2_b32 v[98:99], v104 offset0:66 offset1:99
	ds_read2_b32 v[100:101], v104 offset0:132 offset1:165
	s_waitcnt lgkmcnt(2)
	v_cvt_pk_bf16_f32 v96, v102, v103
	s_waitcnt lgkmcnt(1)
	ds_read2_b32 v[102:103], v104 offset0:198 offset1:231
	v_cvt_pk_bf16_f32 v97, v98, v99
	s_waitcnt lgkmcnt(1)
	v_cvt_pk_bf16_f32 v98, v100, v101
	s_waitcnt lgkmcnt(0)
	v_cvt_pk_bf16_f32 v99, v102, v103
	v_add_u32_e32 v100, s94, v152
	v_ashrrev_i32_e32 v101, 31, v100
	v_lshlrev_b64 v[100:101], 11, v[100:101]
	v_lshl_add_u64 v[100:101], s[78:79], 0, v[100:101]
	v_lshl_add_u64 v[100:101], v[100:101], 0, s[8:9]
	v_lshl_add_u64 v[100:101], v[100:101], 0, v[134:135]
	global_store_dwordx4 v[100:101], v[96:99], off
	s_waitcnt lgkmcnt(0)

; #define GAS __attribute__((address_space(1)))
; #define LAS __attribute__((address_space(3)))
; #define LDS_WAIT() asm volatile("s_waitcnt lgkmcnt(0)" ::: "memory")
; __device__ __forceinline__ unsigned pk2(float lo, float hi) { return f2bf(lo) | (f2bf(hi) << 16); }
; __device__ __forceinline__ void p0_item_store(const P0Item& I, const float (&wv)[32], LAS float* scr, int lane) {
; #pragma unroll
;     for (int i = 0; i < 8; ++i) { const int kk = 8 * i + (lane >> 3); const float s = I.scale ? I.scale[I.k0 + kk] : 1.f; LAS float* d = scr + kk * 33 + 4 * (lane & 7);
;         d[0] = wv[4 * i] * s; d[1] = wv[4 * i + 1] * s; d[2] = wv[4 * i + 2] * s; d[3] = wv[4 * i + 3] * s; }
;     LDS_WAIT(); asm volatile("" ::: "memory");
;     const int c = lane & 7;
; #pragma unroll
;     for (int j = 0; j < 4; ++j) { const int n = (lane >> 3) + 8 * j; const int ns = I.perm ? rope_perm(n) : n; const LAS float* s = scr + (8 * c) * 33 + ns;
;         v4u o; o.x = pk2(s[0 * 33], s[1 * 33]); o.y = pk2(s[2 * 33], s[3 * 33]); o.z = pk2(s[4 * 33], s[5 * 33]); o.w = pk2(s[6 * 33], s[7 * 33]);
;         *(GAS v4u*)(I.WT + (size_t)(I.out_row0 + n) * I.K + I.k0 + 8 * c) = o; }
;     LDS_WAIT(); asm volatile("" ::: "memory");
.LBB0_83:
	v_add_u32_e32 v162, 0xc60, v159
	ds_write2_b32 v162, v142, v143 offset1:1
	v_add_u32_e32 v142, 0xc68, v159
	s_add_i32 s95, s13, s64
	ds_write2_b32 v142, v144, v145 offset1:1
	s_waitcnt vmcnt(0)
	v_pk_mul_f32 v[144:145], v[96:97], v[140:141] op_sel_hi:[1,0]
	v_add_u32_e32 v139, 0x1080, v159
	s_cmpk_lt_i32 s95, 0xa10
	ds_write2_b32 v139, v144, v145 offset1:1
	v_pk_mul_f32 v[144:145], v[98:99], v[140:141] op_sel_hi:[1,0]
	v_add_u32_e32 v140, 0x1088, v159
	s_cselect_b64 s[88:89], -1, 0
	ds_write2_b32 v140, v144, v145 offset1:1
	s_and_b64 vcc, s[0:1], s[84:85]
	s_waitcnt lgkmcnt(0)
	v_cndmask_b32_e32 v138, v132, v154, vcc
	v_lshl_add_u32 v138, v138, 2, v153
	ds_read2_b32 v[144:145], v138 offset1:33
	ds_read2_b32 v[166:167], v138 offset0:66 offset1:99
	ds_read2_b32 v[168:169], v138 offset0:198 offset1:231
	s_add_i32 s83, s34, s83
	s_and_b64 s[14:15], s[2:3], s[84:85]
	s_waitcnt lgkmcnt(2)
	v_cvt_pk_bf16_f32 v164, v144, v145
	ds_read2_b32 v[144:145], v138 offset0:132 offset1:165
	s_waitcnt lgkmcnt(2)
	v_cvt_pk_bf16_f32 v165, v166, v167
	s_waitcnt lgkmcnt(0)
	v_cvt_pk_bf16_f32 v166, v144, v145
	v_add_u32_e32 v144, s83, v132
	v_cvt_pk_bf16_f32 v167, v168, v169
	v_ashrrev_i32_e32 v145, 31, v144
	v_cndmask_b32_e64 v138, v149, v155, s[14:15]
	s_ashr_i32 s87, s86, 31
	v_lshlrev_b64 v[168:169], 11, v[144:145]
	v_lshl_add_u32 v138, v138, 2, v153
	s_lshl_b64 s[92:93], s[86:87], 1
	ds_read2_b32 v[170:171], v138 offset1:33
	v_lshl_add_u64 v[168:169], s[78:79], 0, v[168:169]
	v_lshl_add_u64 v[168:169], v[168:169], 0, s[92:93]
	v_lshl_add_u64 v[168:169], v[168:169], 0, v[134:135]
	global_store_dwordx4 v[168:169], v[164:167], off
	ds_read2_b32 v[166:167], v138 offset0:66 offset1:99
	s_waitcnt lgkmcnt(1)
	ds_read2_b32 v[168:169], v138 offset0:132 offset1:165
	v_cvt_pk_bf16_f32 v164, v170, v171
	s_waitcnt lgkmcnt(1)
	ds_read2_b32 v[170:171], v138 offset0:198 offset1:231
	v_cvt_pk_bf16_f32 v165, v166, v167
	s_waitcnt lgkmcnt(1)
	v_cvt_pk_bf16_f32 v166, v168, v169
	s_waitcnt lgkmcnt(0)
	s_and_b64 s[10:11], s[4:5], s[84:85]
	v_add_u32_e32 v168, 8, v144
	v_cvt_pk_bf16_f32 v167, v170, v171
	v_ashrrev_i32_e32 v169, 31, v168
	v_cndmask_b32_e64 v138, v151, v156, s[10:11]
	v_lshlrev_b64 v[168:169], 11, v[168:169]
	v_lshl_add_u32 v138, v138, 2, v153
	ds_read2_b32 v[170:171], v138 offset1:33
	v_lshl_add_u64 v[168:169], s[78:79], 0, v[168:169]
	v_lshl_add_u64 v[168:169], v[168:169], 0, s[92:93]
	v_lshl_add_u64 v[168:169], v[168:169], 0, v[134:135]
	global_store_dwordx4 v[168:169], v[164:167], off
	ds_read2_b32 v[166:167], v138 offset0:66 offset1:99
	s_waitcnt lgkmcnt(1)
	ds_read2_b32 v[168:169], v138 offset0:132 offset1:165
	v_cvt_pk_bf16_f32 v164, v170, v171
	s_waitcnt lgkmcnt(1)
	ds_read2_b32 v[170:171], v138 offset0:198 offset1:231
	v_cvt_pk_bf16_f32 v165, v166, v167
	s_waitcnt lgkmcnt(1)
	v_cvt_pk_bf16_f32 v166, v168, v169
	s_waitcnt lgkmcnt(0)
	s_and_b64 vcc, s[6:7], s[84:85]
	v_add_u32_e32 v168, 16, v144
	v_cvt_pk_bf16_f32 v167, v170, v171
	v_ashrrev_i32_e32 v169, 31, v168
	v_cndmask_b32_e32 v138, v152, v157, vcc
	v_lshlrev_b64 v[168:169], 11, v[168:169]
	v_lshl_add_u32 v138, v138, 2, v153
	ds_read2_b32 v[170:171], v138 offset1:33
	v_lshl_add_u64 v[168:169], s[78:79], 0, v[168:169]
	v_lshl_add_u64 v[168:169], v[168:169], 0, s[92:93]
	v_lshl_add_u64 v[168:169], v[168:169], 0, v[134:135]
	global_store_dwordx4 v[168:169], v[164:167], off
	ds_read2_b32 v[166:167], v138 offset0:66 offset1:99
	s_waitcnt lgkmcnt(1)
	ds_read2_b32 v[168:169], v138 offset0:132 offset1:165
	v_cvt_pk_bf16_f32 v164, v170, v171
	s_waitcnt lgkmcnt(1)
	ds_read2_b32 v[170:171], v138 offset0:198 offset1:231
	v_cvt_pk_bf16_f32 v165, v166, v167
	s_waitcnt lgkmcnt(1)
	v_add_u32_e32 v144, 24, v144
	v_ashrrev_i32_e32 v145, 31, v144
	v_cvt_pk_bf16_f32 v166, v168, v169
	s_waitcnt lgkmcnt(0)
	v_lshlrev_b64 v[144:145], 11, v[144:145]
	v_lshl_add_u64 v[144:145], s[78:79], 0, v[144:145]
	v_lshl_add_u64 v[144:145], v[144:145], 0, s[92:93]
	v_cvt_pk_bf16_f32 v167, v170, v171
	v_lshl_add_u64 v[144:145], v[144:145], 0, v[134:135]
	global_store_dwordx4 v[144:145], v[164:167], off
	s_waitcnt lgkmcnt(0)
	s_cmpk_gt_i32 s95, 0xa0f
	s_cbranch_scc1 .LBB0_98
	s_mul_hi_i32 s10, s95, 0xcb8727c1
	s_add_i32 s10, s10, s95
	s_lshr_b32 s11, s10, 31
	s_ashr_i32 s10, s10, 7
	s_add_i32 s11, s10, s11
	s_mul_i32 s10, s11, 0xa1
	s_sub_i32 s83, s95, s10
	s_lshl_b32 s94, s83, 5
	s_mov_b64 s[84:85], 0
	s_cmpk_lt_i32 s83, 0x50
	s_mov_b32 s10, s94
	s_cbranch_scc1 .LBB0_96
	s_cmpk_gt_u32 s83, 0x6f
	s_mov_b64 s[14:15], -1
	s_cbranch_scc0 .LBB0_94
	s_cmpk_gt_u32 s83, 0x77
	s_mov_b64 s[84:85], -1
	s_cbranch_scc0 .LBB0_92
	s_cmpk_gt_u32 s83, 0x7f
	s_cbranch_scc0 .LBB0_89
	s_add_i32 s10, s94, 32
	s_cmpk_lt_u32 s83, 0xa0
	s_cselect_b32 s10, s10, 0xa00
	s_mov_b64 s[14:15], 0

; #define GAS __attribute__((address_space(1)))
; #define LAS __attribute__((address_space(3)))
; #define LDS_WAIT() asm volatile("s_waitcnt lgkmcnt(0)" ::: "memory")
; __device__ __forceinline__ unsigned f2bf(float f) { unsigned u = __builtin_bit_cast(unsigned, f); return (u + 0x7fffu + ((u >> 16) & 1u)) >> 16; }
; __device__ __forceinline__ unsigned pk2(float lo, float hi) { return f2bf(lo) | (f2bf(hi) << 16); }
; __device__ __forceinline__ void p0_item_store(const P0Item& I, const float (&wv)[32], LAS float* scr, int lane) {
; #pragma unroll
;     for (int i = 0; i < 8; ++i) { const int kk = 8 * i + (lane >> 3); const float s = I.scale ? I.scale[I.k0 + kk] : 1.f; LAS float* d = scr + kk * 33 + 4 * (lane & 7);
;         d[0] = wv[4 * i] * s; d[1] = wv[4 * i + 1] * s; d[2] = wv[4 * i + 2] * s; d[3] = wv[4 * i + 3] * s; }
;     LDS_WAIT(); asm volatile("" ::: "memory");
;     const int c = lane & 7;
; #pragma unroll
;     for (int j = 0; j < 4; ++j) { const int n = (lane >> 3) + 8 * j; const int ns = I.perm ? rope_perm(n) : n; const LAS float* s = scr + (8 * c) * 33 + ns;
;         v4u o; o.x = pk2(s[0 * 33], s[1 * 33]); o.y = pk2(s[2 * 33], s[3 * 33]); o.z = pk2(s[4 * 33], s[5 * 33]); o.w = pk2(s[6 * 33], s[7 * 33]);
;         *(GAS v4u*)(I.WT + (size_t)(I.out_row0 + n) * I.K + I.k0 + 8 * c) = o; }
;     LDS_WAIT(); asm volatile("" ::: "memory");
.LBB0_111:
	s_waitcnt vmcnt(0)
	v_pk_mul_f32 v[144:145], v[88:89], v[138:139] op_sel_hi:[1,0]
	ds_write2_b32 v139, v144, v145 offset1:1
	v_pk_mul_f32 v[144:145], v[90:91], v[138:139] op_sel_hi:[1,0]
	ds_write2_b32 v140, v144, v145 offset1:1
	s_and_b64 vcc, s[0:1], s[80:81]
	s_waitcnt lgkmcnt(0)
	v_cndmask_b32_e32 v138, v132, v154, vcc
	v_lshl_add_u32 v138, v138, 2, v153
	ds_read2_b32 v[144:145], v138 offset1:33
	s_lshl_b64 s[10:11], s[82:83], 1
	s_and_b64 vcc, s[2:3], s[80:81]
	s_waitcnt lgkmcnt(0)
	v_cvt_pk_bf16_f32 v164, v144, v145
	ds_read2_b32 v[144:145], v138 offset0:66 offset1:99
	s_waitcnt lgkmcnt(0)
	v_cvt_pk_bf16_f32 v165, v144, v145
	ds_read2_b32 v[144:145], v138 offset0:132 offset1:165
	s_waitcnt lgkmcnt(0)
	v_cvt_pk_bf16_f32 v166, v144, v145
	ds_read2_b32 v[144:145], v138 offset0:198 offset1:231
	s_waitcnt lgkmcnt(0)
	v_bfe_u32 v138, v144, 16, 1
	v_add3_u32 v138, v144, v138, s62
	v_bfe_u32 v143, v145, 16, 1
	v_add_u32_e32 v144, s65, v132
	v_add3_u32 v143, v145, v143, s62
	v_ashrrev_i32_e32 v145, 31, v144
	v_lshlrev_b64 v[144:145], 11, v[144:145]
	v_lshrrev_b32_e32 v138, 16, v138
	v_lshl_add_u64 v[144:145], s[78:79], 0, v[144:145]
	v_and_or_b32 v167, v143, s63, v138
	v_lshl_add_u64 v[144:145], v[144:145], 0, s[10:11]
	v_cndmask_b32_e32 v138, v149, v155, vcc
	v_lshl_add_u64 v[144:145], v[144:145], 0, v[134:135]
	v_lshl_add_u32 v138, v138, 2, v153
	global_store_dwordx4 v[144:145], v[164:167], off
	ds_read2_b32 v[144:145], v138 offset1:33
	s_and_b64 vcc, s[4:5], s[80:81]
	s_waitcnt lgkmcnt(0)
	v_cvt_pk_bf16_f32 v164, v144, v145
	ds_read2_b32 v[144:145], v138 offset0:66 offset1:99
	s_waitcnt lgkmcnt(0)
	v_cvt_pk_bf16_f32 v165, v144, v145
	ds_read2_b32 v[144:145], v138 offset0:132 offset1:165
	s_waitcnt lgkmcnt(0)
	v_cvt_pk_bf16_f32 v166, v144, v145
	ds_read2_b32 v[144:145], v138 offset0:198 offset1:231
	s_waitcnt lgkmcnt(0)
	v_bfe_u32 v138, v144, 16, 1
	v_add3_u32 v138, v144, v138, s62
	v_bfe_u32 v143, v145, 16, 1
	v_add_u32_e32 v144, s65, v149
	v_add3_u32 v143, v145, v143, s62
	v_ashrrev_i32_e32 v145, 31, v144
	v_lshlrev_b64 v[144:145], 11, v[144:145]
	v_lshrrev_b32_e32 v138, 16, v138
	v_lshl_add_u64 v[144:145], s[78:79], 0, v[144:145]
	v_and_or_b32 v167, v143, s63, v138
	v_lshl_add_u64 v[144:145], v[144:145], 0, s[10:11]
	v_cndmask_b32_e32 v138, v151, v156, vcc
	v_lshl_add_u64 v[144:145], v[144:145], 0, v[134:135]
	v_lshl_add_u32 v138, v138, 2, v153
	global_store_dwordx4 v[144:145], v[164:167], off
	ds_read2_b32 v[144:145], v138 offset1:33
	s_and_b64 vcc, s[6:7], s[80:81]
	s_waitcnt lgkmcnt(0)
	v_cvt_pk_bf16_f32 v164, v144, v145
	ds_read2_b32 v[144:145], v138 offset0:66 offset1:99
	s_waitcnt lgkmcnt(0)
	v_cvt_pk_bf16_f32 v165, v144, v145
	ds_read2_b32 v[144:145], v138 offset0:132 offset1:165
	s_waitcnt lgkmcnt(0)
	v_cvt_pk_bf16_f32 v166, v144, v145
	ds_read2_b32 v[144:145], v138 offset0:198 offset1:231
	s_waitcnt lgkmcnt(0)
	v_bfe_u32 v138, v144, 16, 1
	v_add3_u32 v138, v144, v138, s62
	v_bfe_u32 v143, v145, 16, 1
	v_add_u32_e32 v144, s65, v151
	v_add3_u32 v143, v145, v143, s62
	v_ashrrev_i32_e32 v145, 31, v144
	v_lshlrev_b64 v[144:145], 11, v[144:145]
	v_lshrrev_b32_e32 v138, 16, v138
	v_lshl_add_u64 v[144:145], s[78:79], 0, v[144:145]
	v_and_or_b32 v167, v143, s63, v138
	v_lshl_add_u64 v[144:145], v[144:145], 0, s[10:11]
	v_cndmask_b32_e32 v138, v152, v157, vcc
	v_lshl_add_u64 v[144:145], v[144:145], 0, v[134:135]
	v_lshl_add_u32 v138, v138, 2, v153
	global_store_dwordx4 v[144:145], v[164:167], off
	ds_read2_b32 v[144:145], v138 offset1:33
	s_waitcnt lgkmcnt(0)
	v_cvt_pk_bf16_f32 v164, v144, v145
	ds_read2_b32 v[144:145], v138 offset0:66 offset1:99
	s_waitcnt lgkmcnt(0)
	v_cvt_pk_bf16_f32 v165, v144, v145
	ds_read2_b32 v[144:145], v138 offset0:132 offset1:165
	s_waitcnt lgkmcnt(0)
	v_cvt_pk_bf16_f32 v166, v144, v145
	ds_read2_b32 v[144:145], v138 offset0:198 offset1:231
	s_waitcnt lgkmcnt(0)
	v_bfe_u32 v138, v144, 16, 1
	v_add3_u32 v138, v144, v138, s62
	v_bfe_u32 v143, v145, 16, 1
	v_add_u32_e32 v144, s65, v152
	v_add3_u32 v143, v145, v143, s62
	v_ashrrev_i32_e32 v145, 31, v144
	v_lshlrev_b64 v[144:145], 11, v[144:145]
	v_lshl_add_u64 v[144:145], s[78:79], 0, v[144:145]
	v_lshrrev_b32_e32 v138, 16, v138
	v_lshl_add_u64 v[144:145], v[144:145], 0, s[10:11]
	v_and_or_b32 v167, v143, s63, v138
	v_lshl_add_u64 v[144:145], v[144:145], 0, v[134:135]
	global_store_dwordx4 v[144:145], v[164:167], off
	s_waitcnt lgkmcnt(0)
	s_andn2_b64 vcc, exec, s[88:89]
	s_cbranch_vccnz .LBB0_48

; #define GAS __attribute__((address_space(1)))
; __device__ __forceinline__ void p0_prologue(Frame& F, const Ptrs& P) {
;     ...
;     {
;         f32x4 vb[4][4];
; #pragma unroll
;         for (int r = 0; r < 4; ++r) { const GAS f32x4* xr = (const GAS f32x4*)(P.x + (size_t)(gw + (4 + r) * NGW) * DM) + lane;
; #pragma unroll
;             for (int j = 0; j < 4; ++j) vb[r][j] = xr[64 * j]; }
;         P0_XROWS(va, gw);
;         P0_XROWS(vb, gw + 4 * NGW);
.LBB0_131:
	s_add_u32 s14, s96, 0x180000
	s_addc_u32 s15, s97, 0
	s_add_u32 s20, s96, 0x1400000
	v_readlane_b32 s0, v252, 2
	s_addc_u32 s21, s97, 0
	s_lshl_b32 s0, s0, 5
	s_add_i32 s6, s70, s0
	s_ashr_i32 s7, s6, 31
	s_lshl_b64 s[0:1], s[6:7], 12
	s_add_u32 s0, s16, s0
	s_addc_u32 s1, s17, s1
	s_add_i32 s8, s6, s33
	s_ashr_i32 s9, s8, 31
	v_lshl_add_u64 v[64:65], s[0:1], 0, v[130:131]
	s_lshl_b64 s[0:1], s[8:9], 12
	s_add_u32 s0, s16, s0
	s_addc_u32 s1, s17, s1
	global_load_dwordx4 v[124:127], v[64:65], off
	global_load_dwordx4 v[120:123], v[64:65], off offset:1024
	global_load_dwordx4 v[116:119], v[64:65], off offset:2048
	global_load_dwordx4 v[112:115], v[64:65], off offset:3072
	v_lshl_add_u64 v[64:65], s[0:1], 0, v[130:131]
	s_add_i32 s0, s8, s33
	s_ashr_i32 s1, s0, 31
	s_lshl_b64 s[2:3], s[0:1], 12
	s_add_u32 s2, s16, s2
	s_addc_u32 s3, s17, s3
	s_add_i32 s0, s0, s33
	s_ashr_i32 s1, s0, 31
	s_lshl_b64 s[0:1], s[0:1], 12
	s_add_u32 s0, s16, s0
	global_load_dwordx4 v[108:111], v[64:65], off
	global_load_dwordx4 v[104:107], v[64:65], off offset:1024
	global_load_dwordx4 v[100:103], v[64:65], off offset:2048
	global_load_dwordx4 v[96:99], v[64:65], off offset:3072
	v_lshl_add_u64 v[64:65], s[2:3], 0, v[130:131]
	s_addc_u32 s1, s17, s1
	global_load_dwordx4 v[92:95], v[64:65], off
	global_load_dwordx4 v[88:91], v[64:65], off offset:1024
	global_load_dwordx4 v[84:87], v[64:65], off offset:2048
	global_load_dwordx4 v[80:83], v[64:65], off offset:3072
	v_lshl_add_u64 v[64:65], s[0:1], 0, v[130:131]
	global_load_dwordx4 v[76:79], v[64:65], off
	global_load_dwordx4 v[72:75], v[64:65], off offset:1024
	global_load_dwordx4 v[68:71], v[64:65], off offset:2048
	s_nop 0
	global_load_dwordx4 v[64:67], v[64:65], off offset:3072
	s_waitcnt vmcnt(31)
	v_mul_f32_e32 v132, v61, v61
	v_mul_f32_e32 v133, v63, v63
	v_fmac_f32_e32 v132, v60, v60
	v_fmac_f32_e32 v133, v62, v62
	v_add_f32_e32 v132, v132, v133
	s_waitcnt vmcnt(30)
	v_mul_f32_e32 v133, v57, v57
	v_mul_f32_e32 v135, v59, v59
	v_fmac_f32_e32 v133, v56, v56
	v_fmac_f32_e32 v135, v58, v58
	v_add_f32_e32 v133, v133, v135
	v_mbcnt_lo_u32_b32 v130, -1, 0
	v_add_f32_e32 v132, v132, v133
	s_waitcnt vmcnt(29)
	v_mul_f32_e32 v133, v53, v53
	v_mul_f32_e32 v135, v55, v55
	v_mbcnt_hi_u32_b32 v134, -1, v130
	v_fmac_f32_e32 v133, v52, v52
	v_fmac_f32_e32 v135, v54, v54
	v_and_b32_e32 v130, 64, v134
	v_add_f32_e32 v133, v133, v135
	v_add_u32_e32 v136, 64, v130
	v_xor_b32_e32 v130, 1, v134
	v_add_f32_e32 v132, v132, v133
	s_waitcnt vmcnt(28)
	v_mul_f32_e32 v133, v49, v49
	v_mul_f32_e32 v135, v51, v51
	v_cmp_lt_i32_e32 vcc, v130, v136
	v_fmac_f32_e32 v133, v48, v48
	v_fmac_f32_e32 v135, v50, v50
	v_cndmask_b32_e32 v130, v134, v130, vcc
	v_add_f32_e32 v133, v133, v135
	v_lshlrev_b32_e32 v130, 2, v130
	v_add_f32_e32 v132, v132, v133
	ds_bpermute_b32 v133, v130, v132
	v_xor_b32_e32 v131, 2, v134
	v_cmp_lt_i32_e32 vcc, v131, v136
	v_xor_b32_e32 v135, 4, v134
	v_cndmask_b32_e32 v131, v134, v131, vcc
	v_lshlrev_b32_e32 v131, 2, v131
	s_waitcnt lgkmcnt(0)
	v_add_f32_e32 v133, v132, v133
	ds_bpermute_b32 v137, v131, v133
	v_cmp_lt_i32_e32 vcc, v135, v136
	s_movk_i32 s16, 0x7fff
	v_cndmask_b32_e32 v132, v134, v135, vcc
	v_lshlrev_b32_e32 v132, 2, v132
	s_waitcnt lgkmcnt(0)
	v_add_f32_e32 v137, v133, v137
	ds_bpermute_b32 v138, v132, v137
	v_xor_b32_e32 v135, 8, v134
	v_cmp_lt_i32_e32 vcc, v135, v136
	v_cndmask_b32_e32 v133, v134, v135, vcc
	v_lshlrev_b32_e32 v133, 2, v133
	s_waitcnt lgkmcnt(0)
	v_add_f32_e32 v137, v137, v138
	ds_bpermute_b32 v138, v133, v137
	v_xor_b32_e32 v135, 16, v134
	v_cmp_lt_i32_e32 vcc, v135, v136
	s_mov_b32 s17, 0xffff0000
	v_cndmask_b32_e32 v135, v134, v135, vcc
	v_lshlrev_b32_e32 v135, 2, v135
	s_waitcnt lgkmcnt(0)
	v_add_f32_e32 v137, v137, v138
	ds_bpermute_b32 v138, v135, v137
	s_lshl_b64 s[4:5], s[70:71], 11
	v_cvt_pk_bf16_f32 v60, v60, v61
	v_xor_b32_e32 v139, 32, v134
	s_add_u32 s2, s20, s4
	v_cmp_lt_i32_e32 vcc, v139, v136
	s_addc_u32 s3, s21, s5
	v_cndmask_b32_e32 v134, v134, v139, vcc
	s_waitcnt lgkmcnt(0)
	v_add_f32_e32 v136, v137, v138
	v_lshl_add_u64 v[138:139], v[128:129], 3, s[2:3]
	v_cvt_pk_bf16_f32 v61, v62, v63
	global_store_dwordx2 v[138:139], v[60:61], off
	v_cvt_pk_bf16_f32 v56, v56, v57
	v_cvt_pk_bf16_f32 v57, v58, v59
	global_store_dwordx2 v[138:139], v[56:57], off offset:512
	v_cvt_pk_bf16_f32 v52, v52, v53
	v_cvt_pk_bf16_f32 v53, v54, v55
	global_store_dwordx2 v[138:139], v[52:53], off offset:1024
	v_lshlrev_b32_e32 v134, 2, v134
	ds_bpermute_b32 v137, v134, v136
	v_cvt_pk_bf16_f32 v48, v48, v49
	v_cmp_eq_u32_e64 s[0:1], 0, v128
	v_cvt_pk_bf16_f32 v49, v50, v51
	global_store_dwordx2 v[138:139], v[48:49], off offset:1536
	s_and_saveexec_b64 s[10:11], s[0:1]
	s_cbranch_execz .LBB0_133
	s_waitcnt lgkmcnt(0)
	v_add_f32_e32 v48, v136, v137
	v_mov_b32_e32 v49, 0x358637bd
	v_fmac_f32_e32 v49, 0x3a800000, v48
	s_mov_b32 s2, 0xf800000
	v_mul_f32_e32 v48, 0x4f800000, v49
	v_cmp_gt_f32_e32 vcc, s2, v49
	s_nop 1
	v_cndmask_b32_e32 v48, v49, v48, vcc
	v_sqrt_f32_e32 v49, v48
	s_nop 0
	v_add_u32_e32 v50, -1, v49
	v_fma_f32 v51, -v50, v49, v48
	v_cmp_ge_f32_e64 s[2:3], 0, v51
	v_add_u32_e32 v51, 1, v49
	s_nop 0
	v_cndmask_b32_e64 v50, v49, v50, s[2:3]
	v_fma_f32 v49, -v51, v49, v48
	v_cmp_lt_f32_e64 s[2:3], 0, v49
	s_nop 1
	v_cndmask_b32_e64 v49, v50, v51, s[2:3]
	v_mul_f32_e32 v50, 0x37800000, v49
	v_cndmask_b32_e32 v49, v49, v50, vcc
	v_mov_b32_e32 v50, 0x260
	v_cmp_class_f32_e32 vcc, v48, v50
	s_nop 1
	v_cndmask_b32_e32 v48, v49, v48, vcc
	v_div_scale_f32 v49, s[2:3], v48, v48, 1.0
	v_rcp_f32_e32 v50, v49
	s_lshl_b64 s[2:3], s[70:71], 2
	s_add_u32 s2, s14, s2
	s_addc_u32 s3, s15, s3
	v_fma_f32 v51, -v49, v50, 1.0
	v_fmac_f32_e32 v50, v51, v50
	v_div_scale_f32 v51, vcc, 1.0, v48, 1.0
	v_mul_f32_e32 v52, v51, v50
	v_fma_f32 v53, -v49, v52, v51
	v_fmac_f32_e32 v52, v53, v50
	v_fma_f32 v49, -v49, v52, v51
	v_div_fmas_f32 v49, v49, v50, v52
	v_div_fixup_f32 v48, v49, v48, 1.0
	v_mov_b32_e32 v49, 0
	global_store_dword v49, v48, s[2:3]
.LBB0_133:
	s_or_b64 exec, exec, s[10:11]
	s_waitcnt vmcnt(31)
	v_mul_f32_e32 v48, v45, v45
	v_mul_f32_e32 v49, v47, v47
	v_fmac_f32_e32 v48, v44, v44
	v_fmac_f32_e32 v49, v46, v46
	v_add_f32_e32 v48, v48, v49
	s_waitcnt vmcnt(30)
	v_mul_f32_e32 v49, v41, v41
	v_mul_f32_e32 v50, v43, v43
	v_fmac_f32_e32 v49, v40, v40
	v_fmac_f32_e32 v50, v42, v42
	v_add_f32_e32 v49, v49, v50
	v_add_f32_e32 v48, v48, v49
	s_waitcnt vmcnt(29)
	v_mul_f32_e32 v49, v37, v37
	v_mul_f32_e32 v50, v39, v39
	v_fmac_f32_e32 v49, v36, v36
	v_fmac_f32_e32 v50, v38, v38
	v_add_f32_e32 v49, v49, v50
	v_add_f32_e32 v48, v48, v49
	s_waitcnt vmcnt(28)
	v_mul_f32_e32 v49, v33, v33
	v_mul_f32_e32 v50, v35, v35
	v_fmac_f32_e32 v49, v32, v32
	v_fmac_f32_e32 v50, v34, v34
	v_add_f32_e32 v49, v49, v50
	v_add_f32_e32 v48, v48, v49
	ds_bpermute_b32 v49, v130, v48
	s_waitcnt lgkmcnt(0)
	v_add_f32_e32 v48, v48, v49
	ds_bpermute_b32 v49, v131, v48
	s_lshl_b64 s[2:3], s[76:77], 11
	v_cvt_pk_bf16_f32 v44, v44, v45
	s_waitcnt lgkmcnt(0)
	v_add_f32_e32 v48, v48, v49
	s_add_u32 s2, s20, s2
	ds_bpermute_b32 v49, v132, v48
	s_addc_u32 s3, s21, s3
	v_lshl_add_u64 v[50:51], v[128:129], 3, s[2:3]
	v_cvt_pk_bf16_f32 v45, v46, v47
	global_store_dwordx2 v[50:51], v[44:45], off
	s_waitcnt lgkmcnt(0)
	v_add_f32_e32 v48, v48, v49
	v_cvt_pk_bf16_f32 v40, v40, v41
	ds_bpermute_b32 v49, v133, v48
	v_cvt_pk_bf16_f32 v41, v42, v43
	global_store_dwordx2 v[50:51], v[40:41], off offset:512
	s_waitcnt lgkmcnt(0)
	v_add_f32_e32 v48, v48, v49
	ds_bpermute_b32 v49, v135, v48
	v_cvt_pk_bf16_f32 v36, v36, v37
	v_cvt_pk_bf16_f32 v37, v38, v39
	global_store_dwordx2 v[50:51], v[36:37], off offset:1024
	s_waitcnt lgkmcnt(0)
	v_add_f32_e32 v48, v48, v49
	ds_bpermute_b32 v49, v134, v48
	v_cvt_pk_bf16_f32 v32, v32, v33
	v_cvt_pk_bf16_f32 v33, v34, v35
	global_store_dwordx2 v[50:51], v[32:33], off offset:1536
	s_and_saveexec_b64 s[10:11], s[0:1]
	s_cbranch_execz .LBB0_135
	s_waitcnt lgkmcnt(0)
	v_add_f32_e32 v32, v48, v49
	v_mov_b32_e32 v33, 0x358637bd
	v_fmac_f32_e32 v33, 0x3a800000, v32
	s_mov_b32 s2, 0xf800000
	v_mul_f32_e32 v32, 0x4f800000, v33
	v_cmp_gt_f32_e32 vcc, s2, v33
	s_nop 1
	v_cndmask_b32_e32 v32, v33, v32, vcc
	v_sqrt_f32_e32 v33, v32
	s_nop 0
	v_add_u32_e32 v34, -1, v33
	v_fma_f32 v35, -v34, v33, v32
	v_cmp_ge_f32_e64 s[2:3], 0, v35
	v_add_u32_e32 v35, 1, v33
	s_nop 0
	v_cndmask_b32_e64 v34, v33, v34, s[2:3]
	v_fma_f32 v33, -v35, v33, v32
	v_cmp_lt_f32_e64 s[2:3], 0, v33
	s_nop 1
	v_cndmask_b32_e64 v33, v34, v35, s[2:3]
	v_mul_f32_e32 v34, 0x37800000, v33
	v_cndmask_b32_e32 v33, v33, v34, vcc
	v_mov_b32_e32 v34, 0x260
	v_cmp_class_f32_e32 vcc, v32, v34
	s_nop 1
	v_cndmask_b32_e32 v32, v33, v32, vcc
	v_div_scale_f32 v33, s[2:3], v32, v32, 1.0
	v_rcp_f32_e32 v34, v33
	s_lshl_b64 s[2:3], s[76:77], 2
	s_add_u32 s2, s14, s2
	s_addc_u32 s3, s15, s3
	v_fma_f32 v35, -v33, v34, 1.0
	v_fmac_f32_e32 v34, v35, v34
	v_div_scale_f32 v35, vcc, 1.0, v32, 1.0
	v_mul_f32_e32 v36, v35, v34
	v_fma_f32 v37, -v33, v36, v35
	v_fmac_f32_e32 v36, v37, v34
	v_fma_f32 v33, -v33, v36, v35
	v_div_fmas_f32 v33, v33, v34, v36
	v_div_fixup_f32 v32, v33, v32, 1.0
	v_mov_b32_e32 v33, 0
	global_store_dword v33, v32, s[2:3]
.LBB0_135:
	s_or_b64 exec, exec, s[10:11]
	s_waitcnt vmcnt(31)
	v_mul_f32_e32 v32, v29, v29
	v_mul_f32_e32 v33, v31, v31
	v_fmac_f32_e32 v32, v28, v28
	v_fmac_f32_e32 v33, v30, v30
	v_add_f32_e32 v32, v32, v33
	s_waitcnt vmcnt(30)
	v_mul_f32_e32 v33, v25, v25
	v_mul_f32_e32 v34, v27, v27
	v_fmac_f32_e32 v33, v24, v24
	v_fmac_f32_e32 v34, v26, v26
	v_add_f32_e32 v33, v33, v34
	v_add_f32_e32 v32, v32, v33
	s_waitcnt vmcnt(29)
	v_mul_f32_e32 v33, v21, v21
	v_mul_f32_e32 v34, v23, v23
	v_fmac_f32_e32 v33, v20, v20
	v_fmac_f32_e32 v34, v22, v22
	v_add_f32_e32 v33, v33, v34
	v_add_f32_e32 v32, v32, v33
	s_waitcnt vmcnt(28)
	v_mul_f32_e32 v33, v17, v17
	v_mul_f32_e32 v34, v19, v19
	v_fmac_f32_e32 v33, v16, v16
	v_fmac_f32_e32 v34, v18, v18
	v_add_f32_e32 v33, v33, v34
	v_add_f32_e32 v32, v32, v33
	ds_bpermute_b32 v33, v130, v32
	s_waitcnt lgkmcnt(0)
	v_add_f32_e32 v32, v32, v33
	ds_bpermute_b32 v33, v131, v32
	s_lshl_b64 s[2:3], s[74:75], 11
	v_cvt_pk_bf16_f32 v28, v28, v29
	s_waitcnt lgkmcnt(0)
	v_add_f32_e32 v32, v32, v33
	s_add_u32 s2, s20, s2
	ds_bpermute_b32 v33, v132, v32
	s_addc_u32 s3, s21, s3
	v_lshl_add_u64 v[34:35], v[128:129], 3, s[2:3]
	v_cvt_pk_bf16_f32 v29, v30, v31
	global_store_dwordx2 v[34:35], v[28:29], off
	s_waitcnt lgkmcnt(0)
	v_add_f32_e32 v32, v32, v33
	v_cvt_pk_bf16_f32 v24, v24, v25
	ds_bpermute_b32 v33, v133, v32
	v_cvt_pk_bf16_f32 v25, v26, v27
	global_store_dwordx2 v[34:35], v[24:25], off offset:512
	s_waitcnt lgkmcnt(0)
	v_add_f32_e32 v32, v32, v33
	ds_bpermute_b32 v33, v135, v32
	v_cvt_pk_bf16_f32 v20, v20, v21
	v_cvt_pk_bf16_f32 v21, v22, v23
	global_store_dwordx2 v[34:35], v[20:21], off offset:1024
	s_waitcnt lgkmcnt(0)
	v_add_f32_e32 v32, v32, v33
	ds_bpermute_b32 v33, v134, v32
	v_cvt_pk_bf16_f32 v16, v16, v17
	v_cvt_pk_bf16_f32 v17, v18, v19
	global_store_dwordx2 v[34:35], v[16:17], off offset:1536
	s_and_saveexec_b64 s[10:11], s[0:1]
	v_readlane_b32 s71, v252, 13
	s_cbranch_execz .LBB0_137
	s_waitcnt lgkmcnt(0)
	v_add_f32_e32 v16, v32, v33
	v_mov_b32_e32 v17, 0x358637bd
	v_fmac_f32_e32 v17, 0x3a800000, v16
	s_mov_b32 s2, 0xf800000
	v_mul_f32_e32 v16, 0x4f800000, v17
	v_cmp_gt_f32_e32 vcc, s2, v17
	s_nop 1
	v_cndmask_b32_e32 v16, v17, v16, vcc
	v_sqrt_f32_e32 v17, v16
	s_nop 0
	v_add_u32_e32 v18, -1, v17
	v_fma_f32 v19, -v18, v17, v16
	v_cmp_ge_f32_e64 s[2:3], 0, v19
	v_add_u32_e32 v19, 1, v17
	s_nop 0
	v_cndmask_b32_e64 v18, v17, v18, s[2:3]
	v_fma_f32 v17, -v19, v17, v16
	v_cmp_lt_f32_e64 s[2:3], 0, v17
	s_nop 1
	v_cndmask_b32_e64 v17, v18, v19, s[2:3]
	v_mul_f32_e32 v18, 0x37800000, v17
	v_cndmask_b32_e32 v17, v17, v18, vcc
	v_mov_b32_e32 v18, 0x260
	v_cmp_class_f32_e32 vcc, v16, v18
	s_nop 1
	v_cndmask_b32_e32 v16, v17, v16, vcc
	v_div_scale_f32 v17, s[2:3], v16, v16, 1.0
	v_rcp_f32_e32 v18, v17
	s_lshl_b64 s[2:3], s[74:75], 2
	s_add_u32 s2, s14, s2
	s_addc_u32 s3, s15, s3
	v_fma_f32 v19, -v17, v18, 1.0
	v_fmac_f32_e32 v18, v19, v18
	v_div_scale_f32 v19, vcc, 1.0, v16, 1.0
	v_mul_f32_e32 v20, v19, v18
	v_fma_f32 v21, -v17, v20, v19
	v_fmac_f32_e32 v20, v21, v18
	v_fma_f32 v17, -v17, v20, v19
	v_div_fmas_f32 v17, v17, v18, v20
	v_div_fixup_f32 v16, v17, v16, 1.0
	v_mov_b32_e32 v17, 0
	global_store_dword v17, v16, s[2:3]
; __device__ __forceinline__ unsigned f2bf(float f) { unsigned u = __builtin_bit_cast(unsigned, f); return (u + 0x7fffu + ((u >> 16) & 1u)) >> 16; }
; __device__ __forceinline__ unsigned pk2(float lo, float hi) { return f2bf(lo) | (f2bf(hi) << 16); }
.LBB0_137:
	s_or_b64 exec, exec, s[10:11]
	s_waitcnt vmcnt(31)
	v_mul_f32_e32 v16, v13, v13
	v_mul_f32_e32 v17, v15, v15
	v_fmac_f32_e32 v16, v12, v12
	v_fmac_f32_e32 v17, v14, v14
	v_add_f32_e32 v16, v16, v17
	s_waitcnt vmcnt(30)
	v_mul_f32_e32 v17, v9, v9
	v_mul_f32_e32 v18, v11, v11
	v_fmac_f32_e32 v17, v8, v8
	v_fmac_f32_e32 v18, v10, v10
	v_add_f32_e32 v17, v17, v18
	v_add_f32_e32 v16, v16, v17
	s_waitcnt vmcnt(29)
	v_mul_f32_e32 v17, v5, v5
	v_mul_f32_e32 v18, v7, v7
	v_fmac_f32_e32 v17, v4, v4
	v_fmac_f32_e32 v18, v6, v6
	v_add_f32_e32 v17, v17, v18
	v_add_f32_e32 v16, v16, v17
	s_waitcnt vmcnt(28)
	v_mul_f32_e32 v17, v1, v1
	v_mul_f32_e32 v18, v3, v3
	v_fmac_f32_e32 v17, v0, v0
	v_fmac_f32_e32 v18, v2, v2
	v_add_f32_e32 v17, v17, v18
	v_add_f32_e32 v16, v16, v17
	ds_bpermute_b32 v17, v130, v16
	s_waitcnt lgkmcnt(0)
	v_add_f32_e32 v16, v16, v17
	ds_bpermute_b32 v17, v131, v16
	s_lshl_b64 s[2:3], s[72:73], 11
	v_cvt_pk_bf16_f32 v12, v12, v13
	s_waitcnt lgkmcnt(0)
	v_add_f32_e32 v16, v16, v17
	s_add_u32 s2, s20, s2
	ds_bpermute_b32 v17, v132, v16
	s_addc_u32 s3, s21, s3
	v_lshl_add_u64 v[18:19], v[128:129], 3, s[2:3]
	v_cvt_pk_bf16_f32 v13, v14, v15
	global_store_dwordx2 v[18:19], v[12:13], off
	s_waitcnt lgkmcnt(0)
	v_add_f32_e32 v16, v16, v17
	v_cvt_pk_bf16_f32 v8, v8, v9
	ds_bpermute_b32 v17, v133, v16
	v_cvt_pk_bf16_f32 v9, v10, v11
	global_store_dwordx2 v[18:19], v[8:9], off offset:512
	s_waitcnt lgkmcnt(0)
	v_add_f32_e32 v16, v16, v17
	ds_bpermute_b32 v17, v135, v16
	v_cvt_pk_bf16_f32 v4, v4, v5
	v_cvt_pk_bf16_f32 v5, v6, v7
	global_store_dwordx2 v[18:19], v[4:5], off offset:1024
	s_waitcnt lgkmcnt(0)
	v_add_f32_e32 v16, v16, v17
	ds_bpermute_b32 v17, v134, v16
	v_cvt_pk_bf16_f32 v0, v0, v1
	v_cvt_pk_bf16_f32 v1, v2, v3
	global_store_dwordx2 v[18:19], v[0:1], off offset:1536
	s_and_saveexec_b64 s[10:11], s[0:1]
	s_cbranch_execz .LBB0_139
	s_waitcnt lgkmcnt(0)
	v_add_f32_e32 v0, v16, v17
	v_mov_b32_e32 v1, 0x358637bd
	v_fmac_f32_e32 v1, 0x3a800000, v0
	s_mov_b32 s2, 0xf800000
	v_mul_f32_e32 v0, 0x4f800000, v1
	v_cmp_gt_f32_e32 vcc, s2, v1
	s_nop 1
	v_cndmask_b32_e32 v0, v1, v0, vcc
	v_sqrt_f32_e32 v1, v0
	s_nop 0
	v_add_u32_e32 v2, -1, v1
	v_fma_f32 v3, -v2, v1, v0
	v_cmp_ge_f32_e64 s[2:3], 0, v3
	v_add_u32_e32 v3, 1, v1
	s_nop 0
	v_cndmask_b32_e64 v2, v1, v2, s[2:3]
	v_fma_f32 v1, -v3, v1, v0
	v_cmp_lt_f32_e64 s[2:3], 0, v1
	s_nop 1
	v_cndmask_b32_e64 v1, v2, v3, s[2:3]
	v_mul_f32_e32 v2, 0x37800000, v1
	v_cndmask_b32_e32 v1, v1, v2, vcc
	v_mov_b32_e32 v2, 0x260
	v_cmp_class_f32_e32 vcc, v0, v2
	s_nop 1
	v_cndmask_b32_e32 v0, v1, v0, vcc
	v_div_scale_f32 v1, s[2:3], v0, v0, 1.0
	v_rcp_f32_e32 v2, v1
	s_lshl_b64 s[2:3], s[72:73], 2
	s_add_u32 s2, s14, s2
	s_addc_u32 s3, s15, s3
	v_fma_f32 v3, -v1, v2, 1.0
	v_fmac_f32_e32 v2, v3, v2
	v_div_scale_f32 v3, vcc, 1.0, v0, 1.0
	v_mul_f32_e32 v4, v3, v2
	v_fma_f32 v5, -v1, v4, v3
	v_fmac_f32_e32 v4, v5, v2
	v_fma_f32 v1, -v1, v4, v3
	v_div_fmas_f32 v1, v1, v2, v4
	v_div_fixup_f32 v0, v1, v0, 1.0
	v_mov_b32_e32 v1, 0
	global_store_dword v1, v0, s[2:3]
.LBB0_139:
	s_or_b64 exec, exec, s[10:11]
	s_waitcnt vmcnt(31)
	v_mul_f32_e32 v0, v125, v125
	v_mul_f32_e32 v1, v127, v127
	v_fmac_f32_e32 v0, v124, v124
	v_fmac_f32_e32 v1, v126, v126
	v_add_f32_e32 v0, v0, v1
	s_waitcnt vmcnt(30)
	v_mul_f32_e32 v1, v121, v121
	v_mul_f32_e32 v2, v123, v123
	v_fmac_f32_e32 v1, v120, v120
	v_fmac_f32_e32 v2, v122, v122
	v_add_f32_e32 v1, v1, v2
	v_add_f32_e32 v0, v0, v1
	s_waitcnt vmcnt(29)
	v_mul_f32_e32 v1, v117, v117
	v_mul_f32_e32 v2, v119, v119
	v_fmac_f32_e32 v1, v116, v116
	v_fmac_f32_e32 v2, v118, v118
	v_add_f32_e32 v1, v1, v2
	v_add_f32_e32 v0, v0, v1
	s_waitcnt vmcnt(28)
	v_mul_f32_e32 v1, v113, v113
	v_mul_f32_e32 v2, v115, v115
	v_fmac_f32_e32 v1, v112, v112
	v_fmac_f32_e32 v2, v114, v114
	v_add_f32_e32 v1, v1, v2
	v_add_f32_e32 v0, v0, v1
	ds_bpermute_b32 v1, v130, v0
	s_waitcnt lgkmcnt(0)
	v_add_f32_e32 v0, v0, v1
	ds_bpermute_b32 v1, v131, v0
	s_lshl_b64 s[2:3], s[6:7], 11
	v_cvt_pk_bf16_f32 v4, v124, v125
	s_waitcnt lgkmcnt(0)
	v_add_f32_e32 v0, v0, v1
	s_add_u32 s2, s20, s2
	ds_bpermute_b32 v1, v132, v0
	s_addc_u32 s3, s21, s3
	v_lshl_add_u64 v[2:3], v[128:129], 3, s[2:3]
	v_cvt_pk_bf16_f32 v5, v126, v127
	global_store_dwordx2 v[2:3], v[4:5], off
	s_waitcnt lgkmcnt(0)
	v_add_f32_e32 v0, v0, v1
	v_cvt_pk_bf16_f32 v4, v120, v121
	ds_bpermute_b32 v1, v133, v0
	v_cvt_pk_bf16_f32 v5, v122, v123
	global_store_dwordx2 v[2:3], v[4:5], off offset:512
	s_waitcnt lgkmcnt(0)
	v_add_f32_e32 v0, v0, v1
	ds_bpermute_b32 v1, v135, v0
	v_cvt_pk_bf16_f32 v4, v116, v117
	v_cvt_pk_bf16_f32 v5, v118, v119
	global_store_dwordx2 v[2:3], v[4:5], off offset:1024
	s_waitcnt lgkmcnt(0)
	v_add_f32_e32 v0, v0, v1
	ds_bpermute_b32 v1, v134, v0
	v_cvt_pk_bf16_f32 v4, v112, v113
	v_cvt_pk_bf16_f32 v5, v114, v115
	global_store_dwordx2 v[2:3], v[4:5], off offset:1536
	s_and_saveexec_b64 s[10:11], s[0:1]
	s_cbranch_execz .LBB0_141
	s_waitcnt lgkmcnt(0)
	v_add_f32_e32 v0, v0, v1
	v_mov_b32_e32 v1, 0x358637bd
	v_fmac_f32_e32 v1, 0x3a800000, v0
	s_mov_b32 s2, 0xf800000
	v_mul_f32_e32 v0, 0x4f800000, v1
	v_cmp_gt_f32_e32 vcc, s2, v1
	s_nop 1
	v_cndmask_b32_e32 v0, v1, v0, vcc
	v_sqrt_f32_e32 v1, v0
	s_nop 0
	v_add_u32_e32 v2, -1, v1
	v_fma_f32 v3, -v2, v1, v0
	v_cmp_ge_f32_e64 s[2:3], 0, v3
	v_add_u32_e32 v3, 1, v1
	s_nop 0
	v_cndmask_b32_e64 v2, v1, v2, s[2:3]
	v_fma_f32 v1, -v3, v1, v0
	v_cmp_lt_f32_e64 s[2:3], 0, v1
	s_nop 1
	v_cndmask_b32_e64 v1, v2, v3, s[2:3]
	v_mul_f32_e32 v2, 0x37800000, v1
	v_cndmask_b32_e32 v1, v1, v2, vcc
	v_mov_b32_e32 v2, 0x260
	v_cmp_class_f32_e32 vcc, v0, v2
	s_nop 1
	v_cndmask_b32_e32 v0, v1, v0, vcc
	v_div_scale_f32 v1, s[2:3], v0, v0, 1.0
	v_rcp_f32_e32 v2, v1
	s_lshl_b64 s[2:3], s[6:7], 2
	s_add_u32 s2, s14, s2
	s_addc_u32 s3, s15, s3
	v_fma_f32 v3, -v1, v2, 1.0
	v_fmac_f32_e32 v2, v3, v2
	v_div_scale_f32 v3, vcc, 1.0, v0, 1.0
	v_mul_f32_e32 v4, v3, v2
	v_fma_f32 v5, -v1, v4, v3
	v_fmac_f32_e32 v4, v5, v2
	v_fma_f32 v1, -v1, v4, v3
	v_div_fmas_f32 v1, v1, v2, v4
	v_div_fixup_f32 v0, v1, v0, 1.0
	v_mov_b32_e32 v1, 0
	global_store_dword v1, v0, s[2:3]
; __device__ __forceinline__ unsigned f2bf(float f) { unsigned u = __builtin_bit_cast(unsigned, f); return (u + 0x7fffu + ((u >> 16) & 1u)) >> 16; }
; __device__ __forceinline__ unsigned pk2(float lo, float hi) { return f2bf(lo) | (f2bf(hi) << 16); }
.LBB0_141:
	s_or_b64 exec, exec, s[10:11]
	s_waitcnt vmcnt(31)
	v_mul_f32_e32 v0, v109, v109
	s_waitcnt lgkmcnt(0)
	v_mul_f32_e32 v1, v111, v111
	v_fmac_f32_e32 v0, v108, v108
	v_fmac_f32_e32 v1, v110, v110
	v_add_f32_e32 v0, v0, v1
	s_waitcnt vmcnt(30)
	v_mul_f32_e32 v1, v105, v105
	v_mul_f32_e32 v2, v107, v107
	v_fmac_f32_e32 v1, v104, v104
	v_fmac_f32_e32 v2, v106, v106
	v_add_f32_e32 v1, v1, v2
	v_add_f32_e32 v0, v0, v1
	s_waitcnt vmcnt(29)
	v_mul_f32_e32 v1, v101, v101
	v_mul_f32_e32 v2, v103, v103
	v_fmac_f32_e32 v1, v100, v100
	v_fmac_f32_e32 v2, v102, v102
	v_add_f32_e32 v1, v1, v2
	v_add_f32_e32 v0, v0, v1
	s_waitcnt vmcnt(28)
	v_mul_f32_e32 v1, v97, v97
	v_mul_f32_e32 v2, v99, v99
	v_fmac_f32_e32 v1, v96, v96
	v_fmac_f32_e32 v2, v98, v98
	v_add_f32_e32 v1, v1, v2
	v_add_f32_e32 v0, v0, v1
	ds_bpermute_b32 v1, v130, v0
	s_waitcnt lgkmcnt(0)
	v_add_f32_e32 v0, v0, v1
	ds_bpermute_b32 v1, v131, v0
	s_lshl_b64 s[2:3], s[8:9], 11
	v_cvt_pk_bf16_f32 v4, v108, v109
	s_waitcnt lgkmcnt(0)
	v_add_f32_e32 v0, v0, v1
	s_add_u32 s2, s20, s2
	ds_bpermute_b32 v1, v132, v0
	s_addc_u32 s3, s21, s3
	v_lshl_add_u64 v[2:3], v[128:129], 3, s[2:3]
	v_cvt_pk_bf16_f32 v5, v110, v111
	global_store_dwordx2 v[2:3], v[4:5], off
	s_waitcnt lgkmcnt(0)
	v_add_f32_e32 v0, v0, v1
	v_cvt_pk_bf16_f32 v4, v104, v105
	ds_bpermute_b32 v1, v133, v0
	v_cvt_pk_bf16_f32 v5, v106, v107
	global_store_dwordx2 v[2:3], v[4:5], off offset:512
	s_waitcnt lgkmcnt(0)
	v_add_f32_e32 v0, v0, v1
	ds_bpermute_b32 v1, v135, v0
	v_cvt_pk_bf16_f32 v4, v100, v101
	v_cvt_pk_bf16_f32 v5, v102, v103
	global_store_dwordx2 v[2:3], v[4:5], off offset:1024
	s_waitcnt lgkmcnt(0)
	v_add_f32_e32 v0, v0, v1
	ds_bpermute_b32 v1, v134, v0
	v_cvt_pk_bf16_f32 v4, v96, v97
	v_cvt_pk_bf16_f32 v5, v98, v99
	global_store_dwordx2 v[2:3], v[4:5], off offset:1536
	s_and_saveexec_b64 s[10:11], s[0:1]
	s_cbranch_execz .LBB0_143
	s_waitcnt lgkmcnt(0)
	v_add_f32_e32 v0, v0, v1
	v_mov_b32_e32 v1, 0x358637bd
	v_fmac_f32_e32 v1, 0x3a800000, v0
	s_mov_b32 s2, 0xf800000
	v_mul_f32_e32 v0, 0x4f800000, v1
	v_cmp_gt_f32_e32 vcc, s2, v1
	s_nop 1
	v_cndmask_b32_e32 v0, v1, v0, vcc
	v_sqrt_f32_e32 v1, v0
	s_nop 0
	v_add_u32_e32 v2, -1, v1
	v_fma_f32 v3, -v2, v1, v0
	v_cmp_ge_f32_e64 s[2:3], 0, v3
	v_add_u32_e32 v3, 1, v1
	s_nop 0
	v_cndmask_b32_e64 v2, v1, v2, s[2:3]
	v_fma_f32 v1, -v3, v1, v0
	v_cmp_lt_f32_e64 s[2:3], 0, v1
	s_nop 1
	v_cndmask_b32_e64 v1, v2, v3, s[2:3]
	v_mul_f32_e32 v2, 0x37800000, v1
	v_cndmask_b32_e32 v1, v1, v2, vcc
	v_mov_b32_e32 v2, 0x260
	v_cmp_class_f32_e32 vcc, v0, v2
	s_nop 1
	v_cndmask_b32_e32 v0, v1, v0, vcc
	v_div_scale_f32 v1, s[2:3], v0, v0, 1.0
	v_rcp_f32_e32 v2, v1
	s_lshl_b64 s[2:3], s[8:9], 2
	s_add_u32 s2, s14, s2
	s_addc_u32 s3, s15, s3
	v_fma_f32 v3, -v1, v2, 1.0
	v_fmac_f32_e32 v2, v3, v2
	v_div_scale_f32 v3, vcc, 1.0, v0, 1.0
	v_mul_f32_e32 v4, v3, v2
	v_fma_f32 v5, -v1, v4, v3
	v_fmac_f32_e32 v4, v5, v2
	v_fma_f32 v1, -v1, v4, v3
	v_div_fmas_f32 v1, v1, v2, v4
	v_div_fixup_f32 v0, v1, v0, 1.0
	v_mov_b32_e32 v1, 0
	global_store_dword v1, v0, s[2:3]
.LBB0_143:
	s_or_b64 exec, exec, s[10:11]
	s_waitcnt vmcnt(31)
	v_mul_f32_e32 v0, v93, v93
	s_waitcnt lgkmcnt(0)
	v_mul_f32_e32 v1, v95, v95
	v_fmac_f32_e32 v0, v92, v92
	v_fmac_f32_e32 v1, v94, v94
	v_add_f32_e32 v0, v0, v1
	s_waitcnt vmcnt(30)
	v_mul_f32_e32 v1, v89, v89
	v_mul_f32_e32 v2, v91, v91
	v_fmac_f32_e32 v1, v88, v88
	v_fmac_f32_e32 v2, v90, v90
	v_add_f32_e32 v1, v1, v2
	v_add_f32_e32 v0, v0, v1
	s_waitcnt vmcnt(29)
	v_mul_f32_e32 v1, v85, v85
	v_mul_f32_e32 v2, v87, v87
	v_fmac_f32_e32 v1, v84, v84
	v_fmac_f32_e32 v2, v86, v86
	v_add_f32_e32 v1, v1, v2
	v_add_f32_e32 v0, v0, v1
	s_waitcnt vmcnt(28)
	v_mul_f32_e32 v1, v81, v81
	v_mul_f32_e32 v2, v83, v83
	v_fmac_f32_e32 v1, v80, v80
	v_fmac_f32_e32 v2, v82, v82
	v_add_f32_e32 v1, v1, v2
	v_add_f32_e32 v0, v0, v1
	ds_bpermute_b32 v1, v130, v0
	s_movk_i32 s7, 0x7fff
	s_add_i32 s8, s6, s13
	s_waitcnt lgkmcnt(0)
	v_add_f32_e32 v0, v0, v1
	ds_bpermute_b32 v1, v131, v0
	s_ashr_i32 s9, s8, 31
	s_mov_b32 s13, 0xffff0000
	s_lshl_b64 s[2:3], s[8:9], 11
	v_cvt_pk_bf16_f32 v4, v92, v93
	s_waitcnt lgkmcnt(0)
	v_add_f32_e32 v0, v0, v1
	s_add_u32 s2, s20, s2
	ds_bpermute_b32 v1, v132, v0
	s_addc_u32 s3, s21, s3
	v_lshl_add_u64 v[2:3], v[128:129], 3, s[2:3]
	v_cvt_pk_bf16_f32 v5, v94, v95
	global_store_dwordx2 v[2:3], v[4:5], off
	s_waitcnt lgkmcnt(0)
	v_add_f32_e32 v0, v0, v1
	v_cvt_pk_bf16_f32 v4, v88, v89
	ds_bpermute_b32 v1, v133, v0
	v_cvt_pk_bf16_f32 v5, v90, v91
	global_store_dwordx2 v[2:3], v[4:5], off offset:512
	s_waitcnt lgkmcnt(0)
	v_add_f32_e32 v0, v0, v1
	ds_bpermute_b32 v1, v135, v0
	v_cvt_pk_bf16_f32 v4, v84, v85
	v_cvt_pk_bf16_f32 v5, v86, v87
	global_store_dwordx2 v[2:3], v[4:5], off offset:1024
	s_waitcnt lgkmcnt(0)
	v_add_f32_e32 v0, v0, v1
	ds_bpermute_b32 v1, v134, v0
	v_cvt_pk_bf16_f32 v4, v80, v81
	v_cvt_pk_bf16_f32 v5, v82, v83
	global_store_dwordx2 v[2:3], v[4:5], off offset:1536
	s_and_saveexec_b64 s[10:11], s[0:1]
	s_cbranch_execz .LBB0_145
	s_waitcnt lgkmcnt(0)
	v_add_f32_e32 v0, v0, v1
	v_mov_b32_e32 v1, 0x358637bd
	v_fmac_f32_e32 v1, 0x3a800000, v0
	s_mov_b32 s2, 0xf800000
	v_mul_f32_e32 v0, 0x4f800000, v1
	v_cmp_gt_f32_e32 vcc, s2, v1
	s_nop 1
	v_cndmask_b32_e32 v0, v1, v0, vcc
	v_sqrt_f32_e32 v1, v0
	s_nop 0
	v_add_u32_e32 v2, -1, v1
	v_fma_f32 v3, -v2, v1, v0
	v_cmp_ge_f32_e64 s[2:3], 0, v3
	v_add_u32_e32 v3, 1, v1
	s_nop 0
	v_cndmask_b32_e64 v2, v1, v2, s[2:3]
	v_fma_f32 v1, -v3, v1, v0
	v_cmp_lt_f32_e64 s[2:3], 0, v1
	s_nop 1
	v_cndmask_b32_e64 v1, v2, v3, s[2:3]
	v_mul_f32_e32 v2, 0x37800000, v1
	v_cndmask_b32_e32 v1, v1, v2, vcc
	v_mov_b32_e32 v2, 0x260
	v_cmp_class_f32_e32 vcc, v0, v2
	s_nop 1
	v_cndmask_b32_e32 v0, v1, v0, vcc
	v_div_scale_f32 v1, s[2:3], v0, v0, 1.0
	v_rcp_f32_e32 v2, v1
	s_lshl_b64 s[2:3], s[8:9], 2
	s_add_u32 s2, s14, s2
	s_addc_u32 s3, s15, s3
	v_fma_f32 v3, -v1, v2, 1.0
	v_fmac_f32_e32 v2, v3, v2
	v_div_scale_f32 v3, vcc, 1.0, v0, 1.0
	v_mul_f32_e32 v4, v3, v2
	v_fma_f32 v5, -v1, v4, v3
	v_fmac_f32_e32 v4, v5, v2
	v_fma_f32 v1, -v1, v4, v3
	v_div_fmas_f32 v1, v1, v2, v4
	v_div_fixup_f32 v0, v1, v0, 1.0
	v_mov_b32_e32 v1, 0
	global_store_dword v1, v0, s[2:3]
; __device__ __forceinline__ unsigned f2bf(float f) { unsigned u = __builtin_bit_cast(unsigned, f); return (u + 0x7fffu + ((u >> 16) & 1u)) >> 16; }
; __device__ __forceinline__ unsigned pk2(float lo, float hi) { return f2bf(lo) | (f2bf(hi) << 16); }
.LBB0_145:
	s_or_b64 exec, exec, s[10:11]
	s_waitcnt vmcnt(31)
	v_mul_f32_e32 v0, v77, v77
	s_waitcnt lgkmcnt(0)
	v_mul_f32_e32 v1, v79, v79
	v_fmac_f32_e32 v0, v76, v76
	v_fmac_f32_e32 v1, v78, v78
	v_add_f32_e32 v0, v0, v1
	s_waitcnt vmcnt(30)
	v_mul_f32_e32 v1, v73, v73
	v_mul_f32_e32 v2, v75, v75
	v_fmac_f32_e32 v1, v72, v72
	v_fmac_f32_e32 v2, v74, v74
	v_add_f32_e32 v1, v1, v2
	v_add_f32_e32 v0, v0, v1
	s_waitcnt vmcnt(29)
	v_mul_f32_e32 v1, v69, v69
	v_mul_f32_e32 v2, v71, v71
	v_fmac_f32_e32 v1, v68, v68
	v_fmac_f32_e32 v2, v70, v70
	v_add_f32_e32 v1, v1, v2
	v_add_f32_e32 v0, v0, v1
	s_waitcnt vmcnt(28)
	v_mul_f32_e32 v1, v65, v65
	v_mul_f32_e32 v2, v67, v67
	v_fmac_f32_e32 v1, v64, v64
	v_fmac_f32_e32 v2, v66, v66
	v_add_f32_e32 v1, v1, v2
	v_add_f32_e32 v0, v0, v1
	ds_bpermute_b32 v1, v130, v0
	s_add_i32 s2, s6, s12
	s_waitcnt lgkmcnt(0)
	v_add_f32_e32 v0, v0, v1
	ds_bpermute_b32 v1, v131, v0
	s_ashr_i32 s3, s2, 31
	s_lshl_b64 s[8:9], s[2:3], 11
	v_cvt_pk_bf16_f32 v4, v76, v77
	s_waitcnt lgkmcnt(0)
	v_add_f32_e32 v0, v0, v1
	s_add_u32 s8, s20, s8
	ds_bpermute_b32 v1, v132, v0
	s_addc_u32 s9, s21, s9
	v_lshl_add_u64 v[2:3], v[128:129], 3, s[8:9]
	v_cvt_pk_bf16_f32 v5, v78, v79
	global_store_dwordx2 v[2:3], v[4:5], off
	s_waitcnt lgkmcnt(0)
	v_add_f32_e32 v0, v0, v1
	v_cvt_pk_bf16_f32 v4, v72, v73
	ds_bpermute_b32 v1, v133, v0
	v_cvt_pk_bf16_f32 v5, v74, v75
	global_store_dwordx2 v[2:3], v[4:5], off offset:512
	s_waitcnt lgkmcnt(0)
	v_add_f32_e32 v0, v0, v1
	ds_bpermute_b32 v1, v135, v0
	v_cvt_pk_bf16_f32 v4, v68, v69
	v_cvt_pk_bf16_f32 v5, v70, v71
	global_store_dwordx2 v[2:3], v[4:5], off offset:1024
	s_waitcnt lgkmcnt(0)
	v_add_f32_e32 v0, v0, v1
	ds_bpermute_b32 v1, v134, v0
	v_cvt_pk_bf16_f32 v4, v64, v65
	v_cvt_pk_bf16_f32 v5, v66, v67
	global_store_dwordx2 v[2:3], v[4:5], off offset:1536
	s_and_saveexec_b64 s[6:7], s[0:1]
	s_cbranch_execz .LBB0_147
	s_waitcnt lgkmcnt(0)
	v_add_f32_e32 v0, v0, v1
	v_mov_b32_e32 v1, 0x358637bd
	v_fmac_f32_e32 v1, 0x3a800000, v0
	s_mov_b32 s0, 0xf800000
	v_mul_f32_e32 v0, 0x4f800000, v1
	v_cmp_gt_f32_e32 vcc, s0, v1
	s_nop 1
	v_cndmask_b32_e32 v0, v1, v0, vcc
	v_sqrt_f32_e32 v1, v0
	s_nop 0
	v_add_u32_e32 v2, -1, v1
	v_fma_f32 v3, -v2, v1, v0
	v_cmp_ge_f32_e64 s[0:1], 0, v3
	v_add_u32_e32 v3, 1, v1
	s_nop 0
	v_cndmask_b32_e64 v2, v1, v2, s[0:1]
	v_fma_f32 v1, -v3, v1, v0
	v_cmp_lt_f32_e64 s[0:1], 0, v1
	s_nop 1
	v_cndmask_b32_e64 v1, v2, v3, s[0:1]
	v_mul_f32_e32 v2, 0x37800000, v1
	v_cndmask_b32_e32 v1, v1, v2, vcc
	v_mov_b32_e32 v2, 0x260
	v_cmp_class_f32_e32 vcc, v0, v2
	s_nop 1
	v_cndmask_b32_e32 v0, v1, v0, vcc
	v_div_scale_f32 v1, s[0:1], v0, v0, 1.0
	v_rcp_f32_e32 v2, v1
	s_lshl_b64 s[0:1], s[2:3], 2
	s_add_u32 s0, s14, s0
	s_addc_u32 s1, s15, s1
	v_fma_f32 v3, -v1, v2, 1.0
	v_fmac_f32_e32 v2, v3, v2
	v_div_scale_f32 v3, vcc, 1.0, v0, 1.0
	v_mul_f32_e32 v4, v3, v2
	v_fma_f32 v5, -v1, v4, v3
	v_fmac_f32_e32 v4, v5, v2
	v_fma_f32 v1, -v1, v4, v3
	v_div_fmas_f32 v1, v1, v2, v4
	v_div_fixup_f32 v0, v1, v0, 1.0
	v_mov_b32_e32 v1, 0
	global_store_dword v1, v0, s[0:1]
